# attention QK^T: 16 K-fragment LDS reads hoisted into free VGPR quads (12 in flight) instead of one quad with a wait per MFMA
# speedup vs baseline: 1.0028x; 1.0027x over previous
.LBB0_1654:
	v_add_u32_e32 v100, v157, v147
	ds_read_b128 v[80:83], v100
	ds_read_b128 v[84:87], v100 offset:4352
	ds_read_b128 v[88:91], v100 offset:8704
	ds_read_b128 v[92:95], v100 offset:13056
	ds_read_b128 v[200:203], v100 offset:64
	ds_read_b128 v[204:207], v100 offset:4416
	ds_read_b128 v[208:211], v100 offset:8768
	ds_read_b128 v[212:215], v100 offset:13120
	ds_read_b128 v[216:219], v100 offset:128
	ds_read_b128 v[220:223], v100 offset:4480
	ds_read_b128 v[224:227], v100 offset:8832
	ds_read_b128 v[228:231], v100 offset:13184
	s_or_b32 s14, s31, 16
	s_or_b32 s15, s31, 32
	s_or_b32 s16, s31, 48
	s_add_i32 s9, s9, 64
	s_waitcnt lgkmcnt(8)
	v_mfma_f32_16x16x32_bf16 v[80:83], v[8:11], v[80:83], 0
	v_mfma_f32_16x16x32_bf16 v[84:87], v[8:11], v[84:87], 0
	v_mfma_f32_16x16x32_bf16 v[88:91], v[8:11], v[88:91], 0
	v_mfma_f32_16x16x32_bf16 v[92:95], v[8:11], v[92:95], 0
	ds_read_b128 v[232:235], v100 offset:192
	ds_read_b128 v[236:239], v100 offset:4544
	ds_read_b128 v[240:243], v100 offset:8896
	ds_read_b128 v[244:247], v100 offset:13248
	s_waitcnt lgkmcnt(8)
	v_mfma_f32_16x16x32_bf16 v[80:83], v[0:3], v[200:203], v[80:83]
	v_mfma_f32_16x16x32_bf16 v[84:87], v[0:3], v[204:207], v[84:87]
	v_mfma_f32_16x16x32_bf16 v[88:91], v[0:3], v[208:211], v[88:91]
	v_mfma_f32_16x16x32_bf16 v[92:95], v[0:3], v[212:215], v[92:95]
	s_waitcnt lgkmcnt(4)
	v_mfma_f32_16x16x32_bf16 v[80:83], v[4:7], v[216:219], v[80:83]
	v_mfma_f32_16x16x32_bf16 v[84:87], v[4:7], v[220:223], v[84:87]
	v_mfma_f32_16x16x32_bf16 v[88:91], v[4:7], v[224:227], v[88:91]
	v_mfma_f32_16x16x32_bf16 v[92:95], v[4:7], v[228:231], v[92:95]
	s_waitcnt lgkmcnt(0)
	v_mfma_f32_16x16x32_bf16 v[80:83], v[12:15], v[232:235], v[80:83]
	v_mfma_f32_16x16x32_bf16 v[84:87], v[12:15], v[236:239], v[84:87]
	v_mfma_f32_16x16x32_bf16 v[88:91], v[12:15], v[240:243], v[88:91]
	v_mfma_f32_16x16x32_bf16 v[92:95], v[12:15], v[244:247], v[92:95]
	s_nop 7
	s_nop 7
	v_mul_f32_e32 v80, 0x3db504f3, v80
	v_mul_f32_e32 v84, 0x3db504f3, v84
	v_subrev_u32_e32 v96, s31, v175
	v_cmp_gt_u32_e32 vcc, s24, v96
	s_and_b64 vcc, s[12:13], vcc
	v_subrev_u32_e32 v96, s14, v175
	v_cndmask_b32_e32 v80, v80, v173, vcc
	v_cmp_gt_u32_e32 vcc, s24, v96
	s_and_b64 vcc, s[12:13], vcc
	v_subrev_u32_e32 v97, s15, v175
	v_cndmask_b32_e32 v84, v84, v173, vcc
	v_cmp_gt_u32_e32 vcc, s24, v97
	v_mul_f32_e32 v88, 0x3db504f3, v88
	s_and_b64 vcc, s[12:13], vcc
	v_subrev_u32_e32 v97, s16, v175
	v_cndmask_b32_e32 v88, v88, v173, vcc
	v_cmp_gt_u32_e32 vcc, s24, v97
	v_mul_f32_e32 v92, 0x3db504f3, v92
	s_and_b64 vcc, s[12:13], vcc
	v_max3_f32 v96, v80, s25, v84
	v_cndmask_b32_e32 v92, v92, v173, vcc
	v_max3_f32 v96, v96, v88, v92
	s_nop 1
	v_mov_b32_dpp v97, v96 quad_perm:[1,0,3,2] row_mask:0xf bank_mask:0xf bound_ctrl:1
	v_max_f32_e32 v97, v97, v97
	v_max_f32_e32 v96, v96, v97
	s_nop 1
	v_mov_b32_dpp v97, v96 quad_perm:[2,3,0,1] row_mask:0xf bank_mask:0xf bound_ctrl:1
	v_max_f32_e32 v97, v97, v97
	v_max_f32_e32 v96, v96, v97
	s_nop 1
	v_mov_b32_dpp v97, v96 row_half_mirror row_mask:0xf bank_mask:0xf bound_ctrl:1
	v_max_f32_e32 v97, v97, v97
	v_max_f32_e32 v96, v96, v97
	s_nop 1
	v_mov_b32_dpp v97, v96 row_mirror row_mask:0xf bank_mask:0xf bound_ctrl:1
	v_max3_f32 v137, v141, v96, v97
	v_sub_f32_e32 v80, v80, v137
	v_mul_f32_e32 v80, 0x3fb8aa3b, v80
	v_exp_f32_e32 v99, v80
	v_sub_f32_e32 v96, v141, v137
	v_mul_f32_e32 v96, 0x3fb8aa3b, v96
	v_exp_f32_e32 v97, v96
	v_cvt_pk_bf16_f32 v80, v99, s0
	ds_write_b16 v171, v80 offset:35840
	v_sub_f32_e32 v80, v84, v137
	v_mul_f32_e32 v80, 0x3fb8aa3b, v80
	v_exp_f32_e32 v101, v80
	v_subrev_u32_e32 v84, s14, v176
	v_mov_b32_e32 v184, v97
	v_cvt_pk_bf16_f32 v80, v101, s0
	ds_write_b16 v171, v80 offset:35872
	v_sub_f32_e32 v80, v88, v137
	v_mul_f32_e32 v80, 0x3fb8aa3b, v80
	v_exp_f32_e32 v103, v80
	v_subrev_u32_e32 v88, s15, v176
	v_cvt_pk_bf16_f32 v80, v103, s0
	ds_write_b16 v171, v80 offset:35904
	v_sub_f32_e32 v80, v92, v137
	v_mul_f32_e32 v80, 0x3fb8aa3b, v80
	v_exp_f32_e32 v141, v80
	s_nop 0
	v_cvt_pk_bf16_f32 v80, v141, s0
	ds_write_b16 v171, v80 offset:35936
	v_mul_f32_e32 v80, 0x3db504f3, v81
	v_subrev_u32_e32 v81, s31, v176
	v_cmp_gt_u32_e32 vcc, s24, v81
	s_and_b64 vcc, s[12:13], vcc
	v_mul_f32_e32 v81, 0x3db504f3, v85
	v_cndmask_b32_e32 v80, v80, v173, vcc
	v_cmp_gt_u32_e32 vcc, s24, v84
	s_and_b64 vcc, s[12:13], vcc
	v_mul_f32_e32 v85, 0x3db504f3, v89
	v_cndmask_b32_e32 v81, v81, v173, vcc
	v_cmp_gt_u32_e32 vcc, s24, v88
	s_and_b64 vcc, s[12:13], vcc
	v_subrev_u32_e32 v89, s16, v176
	v_cndmask_b32_e32 v85, v85, v173, vcc
	v_cmp_gt_u32_e32 vcc, s24, v89
	v_mul_f32_e32 v88, 0x3db504f3, v93
	s_and_b64 vcc, s[12:13], vcc
	v_max3_f32 v84, v80, s25, v81
	v_cndmask_b32_e32 v88, v88, v173, vcc
	v_max3_f32 v84, v84, v85, v88
	s_nop 1
	v_mov_b32_dpp v89, v84 quad_perm:[1,0,3,2] row_mask:0xf bank_mask:0xf bound_ctrl:1
	v_max_f32_e32 v89, v89, v89
	v_max_f32_e32 v84, v84, v89
	s_nop 1
	v_mov_b32_dpp v89, v84 quad_perm:[2,3,0,1] row_mask:0xf bank_mask:0xf bound_ctrl:1
	v_max_f32_e32 v89, v89, v89
	v_max_f32_e32 v84, v84, v89
	s_nop 1
	v_mov_b32_dpp v89, v84 row_half_mirror row_mask:0xf bank_mask:0xf bound_ctrl:1
	v_max_f32_e32 v89, v89, v89
	v_max_f32_e32 v84, v84, v89
	s_nop 1
	v_mov_b32_dpp v89, v84 row_mirror row_mask:0xf bank_mask:0xf bound_ctrl:1
	v_max3_f32 v135, v140, v84, v89
	v_sub_f32_e32 v80, v80, v135
	v_mul_f32_e32 v80, 0x3fb8aa3b, v80
	v_exp_f32_e32 v98, v80
	v_sub_f32_e32 v84, v140, v135
	v_mul_f32_e32 v84, 0x3fb8aa3b, v84
	v_exp_f32_e32 v96, v84
	v_cvt_pk_bf16_f32 v80, v98, s0
	ds_write_b16 v171, v80 offset:35984
	v_sub_f32_e32 v80, v81, v135
	v_mul_f32_e32 v80, 0x3fb8aa3b, v80
	v_exp_f32_e32 v100, v80
	v_mov_b32_e32 v185, v96
	v_pk_mul_f32 v[92:93], v[16:17], v[184:185]
	v_pk_mul_f32 v[16:17], v[40:41], v[184:185]
	v_cvt_pk_bf16_f32 v80, v100, s0
	ds_write_b16 v171, v80 offset:36016
	v_sub_f32_e32 v80, v85, v135
	v_mul_f32_e32 v80, 0x3fb8aa3b, v80
	v_exp_f32_e32 v102, v80
	v_pk_fma_f32 v[80:81], v[120:121], v[96:97], v[98:99]
	v_subrev_u32_e32 v85, s15, v177
	v_pk_add_f32 v[80:81], v[100:101], v[80:81]
	v_cvt_pk_bf16_f32 v84, v102, s0
	ds_write_b16 v171, v84 offset:36048
	v_sub_f32_e32 v84, v88, v135
	v_mul_f32_e32 v84, 0x3fb8aa3b, v84
	v_exp_f32_e32 v140, v84
	v_pk_add_f32 v[80:81], v[102:103], v[80:81]
	v_mul_f32_e32 v84, 0x3db504f3, v90
	v_pk_mul_f32 v[88:89], v[20:21], v[184:185]
	v_pk_add_f32 v[120:121], v[140:141], v[80:81]
	v_subrev_u32_e32 v81, s31, v177
	v_cvt_pk_bf16_f32 v80, v140, s0
	v_cmp_gt_u32_e32 vcc, s24, v81
	ds_write_b16 v171, v80 offset:36080
	v_mul_f32_e32 v80, 0x3db504f3, v82
	s_and_b64 vcc, s[12:13], vcc
	v_subrev_u32_e32 v82, s14, v177
	v_cndmask_b32_e32 v80, v80, v173, vcc
	v_cmp_gt_u32_e32 vcc, s24, v82
	v_mul_f32_e32 v81, 0x3db504f3, v86
	s_and_b64 vcc, s[12:13], vcc
	v_cndmask_b32_e32 v81, v81, v173, vcc
	v_cmp_gt_u32_e32 vcc, s24, v85
	s_and_b64 vcc, s[12:13], vcc
	v_subrev_u32_e32 v86, s16, v177
	v_cndmask_b32_e32 v84, v84, v173, vcc
	v_cmp_gt_u32_e32 vcc, s24, v86
	v_mul_f32_e32 v85, 0x3db504f3, v94
	s_and_b64 vcc, s[12:13], vcc
	v_max3_f32 v82, v80, s25, v81
	v_cndmask_b32_e32 v85, v85, v173, vcc
	v_max3_f32 v82, v82, v84, v85
	v_pk_mul_f32 v[20:21], v[44:45], v[184:185]
	s_nop 0
	v_mov_b32_dpp v86, v82 quad_perm:[1,0,3,2] row_mask:0xf bank_mask:0xf bound_ctrl:1
	v_max_f32_e32 v86, v86, v86
	v_max_f32_e32 v82, v82, v86
	s_nop 1
	v_mov_b32_dpp v86, v82 quad_perm:[2,3,0,1] row_mask:0xf bank_mask:0xf bound_ctrl:1
	v_max_f32_e32 v86, v86, v86
	v_max_f32_e32 v82, v82, v86
	s_nop 1
	v_mov_b32_dpp v86, v82 row_half_mirror row_mask:0xf bank_mask:0xf bound_ctrl:1
	v_max_f32_e32 v86, v86, v86
	v_max_f32_e32 v82, v82, v86
	s_nop 1
	v_mov_b32_dpp v86, v82 row_mirror row_mask:0xf bank_mask:0xf bound_ctrl:1
	v_max3_f32 v131, v139, v82, v86
	v_sub_f32_e32 v80, v80, v131
	v_mul_f32_e32 v80, 0x3fb8aa3b, v80
	v_exp_f32_e32 v103, v80
	v_sub_f32_e32 v82, v139, v131
	v_mul_f32_e32 v82, 0x3fb8aa3b, v82
	v_exp_f32_e32 v98, v82
	v_cvt_pk_bf16_f32 v80, v103, s0
	ds_write_b16 v171, v80 offset:36128
	v_sub_f32_e32 v80, v81, v131
	v_mul_f32_e32 v80, 0x3fb8aa3b, v80
	v_exp_f32_e32 v139, v80
	v_subrev_u32_e32 v81, s31, v178
	v_cmp_gt_u32_e32 vcc, s24, v81
	s_and_b64 vcc, s[12:13], vcc
	v_cvt_pk_bf16_f32 v80, v139, s0
	ds_write_b16 v171, v80 offset:36160
	v_sub_f32_e32 v80, v84, v131
	v_mul_f32_e32 v80, 0x3fb8aa3b, v80
	v_exp_f32_e32 v141, v80
	v_subrev_u32_e32 v81, s14, v178
	v_subrev_u32_e32 v82, s15, v178
	v_cvt_pk_bf16_f32 v80, v141, s0
	ds_write_b16 v171, v80 offset:36192
	v_sub_f32_e32 v80, v85, v131
	v_mul_f32_e32 v80, 0x3fb8aa3b, v80
	v_exp_f32_e32 v101, v80
	v_pk_mul_f32 v[84:85], v[24:25], v[184:185]
	v_pk_mul_f32 v[24:25], v[36:37], v[184:185]
	v_cvt_pk_bf16_f32 v80, v101, s0
	ds_write_b16 v171, v80 offset:36224
	v_mul_f32_e32 v80, 0x3db504f3, v83
	v_cndmask_b32_e32 v100, v80, v173, vcc
	v_cmp_gt_u32_e32 vcc, s24, v81
	v_mul_f32_e32 v80, 0x3db504f3, v87
	s_and_b64 vcc, s[12:13], vcc
	v_cndmask_b32_e32 v140, v80, v173, vcc
	v_cmp_gt_u32_e32 vcc, s24, v82
	v_mul_f32_e32 v81, 0x3db504f3, v91
	s_and_b64 vcc, s[12:13], vcc
	v_subrev_u32_e32 v82, s16, v178
	v_cndmask_b32_e32 v183, v81, v173, vcc
	v_cmp_gt_u32_e32 vcc, s24, v82
	v_mul_f32_e32 v81, 0x3db504f3, v95
	s_and_b64 vcc, s[12:13], vcc
	v_max3_f32 v80, v100, s25, v140
	v_cndmask_b32_e32 v186, v81, v173, vcc
	v_max3_f32 v80, v80, v183, v186
	s_cmp_lg_u32 s28, s11
	s_nop 0
	v_mov_b32_dpp v81, v80 quad_perm:[1,0,3,2] row_mask:0xf bank_mask:0xf bound_ctrl:1
	v_max_f32_e32 v81, v81, v81
	v_max_f32_e32 v80, v80, v81
	s_nop 1
	v_mov_b32_dpp v81, v80 quad_perm:[2,3,0,1] row_mask:0xf bank_mask:0xf bound_ctrl:1
	v_max_f32_e32 v81, v81, v81
	v_max_f32_e32 v80, v80, v81
	s_nop 1
	v_mov_b32_dpp v81, v80 row_half_mirror row_mask:0xf bank_mask:0xf bound_ctrl:1
	v_max_f32_e32 v81, v81, v81
	v_max_f32_e32 v80, v80, v81
	s_nop 1
	v_mov_b32_dpp v81, v80 row_mirror row_mask:0xf bank_mask:0xf bound_ctrl:1
	v_max3_f32 v133, v138, v80, v81
	v_sub_f32_e32 v80, v138, v133
	v_mul_f32_e32 v80, 0x3fb8aa3b, v80
	v_exp_f32_e32 v99, v80
	v_pk_mul_f32 v[80:81], v[28:29], v[184:185]
	v_pk_mul_f32 v[28:29], v[32:33], v[184:185]
	v_sub_f32_e32 v32, v100, v133
	v_mul_f32_e32 v32, 0x3fb8aa3b, v32
	v_exp_f32_e32 v102, v32
	v_pk_mul_f32 v[82:83], v[30:31], v[98:99]
	v_pk_mul_f32 v[30:31], v[34:35], v[98:99]
	v_mov_b32_e32 v33, v98
	v_cvt_pk_bf16_f32 v32, v102, s0
	ds_write_b16 v171, v32 offset:36272
	v_sub_f32_e32 v32, v140, v133
	v_mul_f32_e32 v32, 0x3fb8aa3b, v32
	v_exp_f32_e32 v138, v32
	v_pk_mul_f32 v[90:91], v[22:23], v[98:99]
	v_pk_mul_f32 v[22:23], v[46:47], v[98:99]
	v_pk_mul_f32 v[86:87], v[26:27], v[98:99]
	v_cvt_pk_bf16_f32 v32, v138, s0
	ds_write_b16 v171, v32 offset:36304
	v_sub_f32_e32 v32, v183, v133
	v_mul_f32_e32 v32, 0x3fb8aa3b, v32
	v_exp_f32_e32 v140, v32
	v_mov_b32_e32 v32, v99
	v_pk_fma_f32 v[32:33], v[118:119], v[32:33], v[102:103]
	v_pk_mul_f32 v[26:27], v[38:39], v[98:99]
	v_cvt_pk_bf16_f32 v34, v140, s0
	ds_write_b16 v171, v34 offset:36336
	v_sub_f32_e32 v34, v186, v133
	v_mul_f32_e32 v34, 0x3fb8aa3b, v34
	v_exp_f32_e32 v100, v34
	v_pk_add_f32 v[32:33], v[138:139], v[32:33]
	v_add_u32_e32 v138, v157, v158
	v_pk_add_f32 v[32:33], v[140:141], v[32:33]
	v_pk_mul_f32 v[94:95], v[18:19], v[98:99]
	v_pk_add_f32 v[118:119], v[100:101], v[32:33]
	v_cvt_pk_bf16_f32 v32, v100, s0
	ds_write_b16 v171, v32 offset:36368
	s_waitcnt lgkmcnt(0)
	s_barrier
	ds_read_b128 v[32:35], v159 offset:35840
	ds_read_b128 v[44:47], v172 offset:19712
	s_waitcnt lgkmcnt(0)
	v_mfma_f32_16x16x32_bf16 v[44:47], v[32:35], v[44:47], v[84:87]
	s_nop 2
	ds_read_b128 v[84:87], v172 offset:22016
	ds_read_b128 v[36:39], v138 offset:17408
	v_pk_mul_f32 v[18:19], v[42:43], v[98:99]
	s_waitcnt lgkmcnt(1)
	v_mfma_f32_16x16x32_bf16 v[80:83], v[32:35], v[84:87], v[80:83]
	ds_read_b128 v[84:87], v138 offset:26624
	ds_read_b128 v[40:43], v172 offset:17408
	s_waitcnt lgkmcnt(1)
	v_mfma_f32_16x16x32_bf16 v[84:87], v[32:35], v[84:87], v[28:31]
	s_nop 2
	ds_read_b128 v[28:31], v138 offset:28928
	s_waitcnt lgkmcnt(1)
	v_mfma_f32_16x16x32_bf16 v[40:43], v[32:35], v[40:43], v[88:91]
	s_waitcnt lgkmcnt(0)
	v_mfma_f32_16x16x32_bf16 v[88:91], v[32:35], v[28:31], v[24:27]
	s_nop 2
	ds_read_b128 v[24:27], v138 offset:31232
	v_mfma_f32_16x16x32_bf16 v[36:39], v[32:35], v[36:39], v[92:95]
	s_waitcnt lgkmcnt(0)
	v_mfma_f32_16x16x32_bf16 v[92:95], v[32:35], v[24:27], v[20:23]
	s_nop 2
	ds_read_b128 v[20:23], v138 offset:33536
	s_waitcnt lgkmcnt(0)
	v_mfma_f32_16x16x32_bf16 v[96:99], v[32:35], v[20:23], v[16:19]
	ds_read_b128 v[100:103], v159 offset:35904
	s_nop 1
	ds_read_b128 v[16:19], v138 offset:17472
	ds_read_b128 v[20:23], v172 offset:17472
	ds_read_b128 v[24:27], v172 offset:19776
	s_waitcnt lgkmcnt(2)
	v_mfma_f32_16x16x32_bf16 v[16:19], v[100:103], v[16:19], v[36:39]
	ds_read_b128 v[28:31], v172 offset:22080
	s_nop 1
	ds_read_b128 v[36:39], v138 offset:28992
	ds_read_b128 v[32:35], v138 offset:26688
	s_waitcnt lgkmcnt(4)
	v_mfma_f32_16x16x32_bf16 v[20:23], v[100:103], v[20:23], v[40:43]
	s_nop 2
	ds_read_b128 v[40:43], v138 offset:31296
	s_waitcnt lgkmcnt(4)
	v_mfma_f32_16x16x32_bf16 v[24:27], v[100:103], v[24:27], v[44:47]
	s_waitcnt lgkmcnt(0)
	v_mfma_f32_16x16x32_bf16 v[44:47], v[100:103], v[40:43], v[92:95]
	ds_read_b128 v[40:43], v138 offset:33600
	v_mfma_f32_16x16x32_bf16 v[28:31], v[100:103], v[28:31], v[80:83]
	v_mfma_f32_16x16x32_bf16 v[32:35], v[100:103], v[32:35], v[84:87]
	v_mfma_f32_16x16x32_bf16 v[36:39], v[100:103], v[36:39], v[88:91]
	s_waitcnt lgkmcnt(0)
	v_mfma_f32_16x16x32_bf16 v[40:43], v[100:103], v[40:43], v[96:99]
	s_cbranch_scc0 .LBB0_1637
	v_mov_b32_e32 v138, v133
	v_mov_b32_e32 v139, v131
	v_mov_b32_e32 v140, v135
	v_mov_b32_e32 v141, v137
	s_branch .LBB0_1642
